# merge-GEMM epilogue rewritten by hand: all gate loads of a sub-unit in flight with counted vmcnt (was one load per round trip)
# speedup vs baseline: 1.0199x; 1.0080x over previous
.LBB0_1100:
	v_lshl_add_u32 v150, s6, 8, v160
	v_lshl_or_b32 v151, s46, 8, v162
	v_lshl_add_u32 v150, v150, 10, v151
	v_lshlrev_b32_e32 v236, 1, v150
	v_add_u32_e32 v237, 0x8000, v236
	v_add_u32_e32 v238, 0x10000, v236
	v_add_u32_e32 v239, 0x18000, v236
	v_add_u32_e32 v146, 0x40000, v236
	v_add_u32_e32 v147, 0x48000, v236
	v_add_u32_e32 v148, 0x50000, v236
	v_add_u32_e32 v149, 0x58000, v236
	s_cmp_lg_u32 s7, 0
	s_cbranch_scc0 .Lepi9_keep
	global_load_dwordx4 v[172:175], v236, s[14:15]
	global_load_dwordx4 v[176:179], v236, s[14:15] offset:256
	global_load_dwordx4 v[180:183], v237, s[14:15]
	global_load_dwordx4 v[184:187], v237, s[14:15] offset:256
	global_load_dwordx4 v[188:191], v238, s[14:15]
	global_load_dwordx4 v[192:195], v238, s[14:15] offset:256
	global_load_dwordx4 v[196:199], v239, s[14:15]
	global_load_dwordx4 v[200:203], v239, s[14:15] offset:256
	global_load_dwordx4 v[204:207], v146, s[14:15]
	global_load_dwordx4 v[208:211], v146, s[14:15] offset:256
	global_load_dwordx4 v[212:215], v147, s[14:15]
	global_load_dwordx4 v[216:219], v147, s[14:15] offset:256
	global_load_dwordx4 v[220:223], v148, s[14:15]
	global_load_dwordx4 v[224:227], v148, s[14:15] offset:256
	global_load_dwordx4 v[228:231], v149, s[14:15]
	global_load_dwordx4 v[232:235], v149, s[14:15] offset:256
	s_waitcnt vmcnt(15)
	v_lshlrev_b32_e32 v154, 16, v172
	v_and_b32_e32 v155, 0xffff0000, v172
	v_lshlrev_b32_e32 v156, 16, v173
	v_and_b32_e32 v157, 0xffff0000, v173
	v_lshlrev_b32_e32 v158, 16, v174
	v_and_b32_e32 v159, 0xffff0000, v174
	v_lshlrev_b32_e32 v164, 16, v175
	v_and_b32_e32 v165, 0xffff0000, v175
	v_pk_mul_f32 v[166:167], v[126:127], v[154:155]
	v_pk_mul_f32 v[168:169], v[128:129], v[156:157]
	v_pk_mul_f32 v[170:171], v[122:123], v[158:159]
	v_pk_mul_f32 v[150:151], v[124:125], v[164:165]
	v_cvt_pk_bf16_f32 v166, v166, v167
	v_cvt_pk_bf16_f32 v167, v168, v169
	v_cvt_pk_bf16_f32 v168, v170, v171
	v_cvt_pk_bf16_f32 v169, v150, v151
	global_store_dwordx4 v236, v[166:169], s[16:17]
	s_waitcnt vmcnt(15)
	v_lshlrev_b32_e32 v154, 16, v176
	v_and_b32_e32 v155, 0xffff0000, v176
	v_lshlrev_b32_e32 v156, 16, v177
	v_and_b32_e32 v157, 0xffff0000, v177
	v_lshlrev_b32_e32 v158, 16, v178
	v_and_b32_e32 v159, 0xffff0000, v178
	v_lshlrev_b32_e32 v164, 16, v179
	v_and_b32_e32 v165, 0xffff0000, v179
	v_pk_mul_f32 v[166:167], v[94:95], v[154:155]
	v_pk_mul_f32 v[168:169], v[96:97], v[156:157]
	v_pk_mul_f32 v[170:171], v[90:91], v[158:159]
	v_pk_mul_f32 v[150:151], v[92:93], v[164:165]
	v_cvt_pk_bf16_f32 v166, v166, v167
	v_cvt_pk_bf16_f32 v167, v168, v169
	v_cvt_pk_bf16_f32 v168, v170, v171
	v_cvt_pk_bf16_f32 v169, v150, v151
	global_store_dwordx4 v236, v[166:169], s[16:17] offset:256
	s_waitcnt vmcnt(15)
	v_lshlrev_b32_e32 v154, 16, v180
	v_and_b32_e32 v155, 0xffff0000, v180
	v_lshlrev_b32_e32 v156, 16, v181
	v_and_b32_e32 v157, 0xffff0000, v181
	v_lshlrev_b32_e32 v158, 16, v182
	v_and_b32_e32 v159, 0xffff0000, v182
	v_lshlrev_b32_e32 v164, 16, v183
	v_and_b32_e32 v165, 0xffff0000, v183
	v_pk_mul_f32 v[166:167], v[118:119], v[154:155]
	v_pk_mul_f32 v[168:169], v[120:121], v[156:157]
	v_pk_mul_f32 v[170:171], v[114:115], v[158:159]
	v_pk_mul_f32 v[150:151], v[116:117], v[164:165]
	v_cvt_pk_bf16_f32 v166, v166, v167
	v_cvt_pk_bf16_f32 v167, v168, v169
	v_cvt_pk_bf16_f32 v168, v170, v171
	v_cvt_pk_bf16_f32 v169, v150, v151
	global_store_dwordx4 v237, v[166:169], s[16:17]
	s_waitcnt vmcnt(15)
	v_lshlrev_b32_e32 v154, 16, v184
	v_and_b32_e32 v155, 0xffff0000, v184
	v_lshlrev_b32_e32 v156, 16, v185
	v_and_b32_e32 v157, 0xffff0000, v185
	v_lshlrev_b32_e32 v158, 16, v186
	v_and_b32_e32 v159, 0xffff0000, v186
	v_lshlrev_b32_e32 v164, 16, v187
	v_and_b32_e32 v165, 0xffff0000, v187
	v_pk_mul_f32 v[166:167], v[86:87], v[154:155]
	v_pk_mul_f32 v[168:169], v[88:89], v[156:157]
	v_pk_mul_f32 v[170:171], v[82:83], v[158:159]
	v_pk_mul_f32 v[150:151], v[84:85], v[164:165]
	v_cvt_pk_bf16_f32 v166, v166, v167
	v_cvt_pk_bf16_f32 v167, v168, v169
	v_cvt_pk_bf16_f32 v168, v170, v171
	v_cvt_pk_bf16_f32 v169, v150, v151
	global_store_dwordx4 v237, v[166:169], s[16:17] offset:256
	s_waitcnt vmcnt(15)
	v_lshlrev_b32_e32 v154, 16, v188
	v_and_b32_e32 v155, 0xffff0000, v188
	v_lshlrev_b32_e32 v156, 16, v189
	v_and_b32_e32 v157, 0xffff0000, v189
	v_lshlrev_b32_e32 v158, 16, v190
	v_and_b32_e32 v159, 0xffff0000, v190
	v_lshlrev_b32_e32 v164, 16, v191
	v_and_b32_e32 v165, 0xffff0000, v191
	v_pk_mul_f32 v[166:167], v[110:111], v[154:155]
	v_pk_mul_f32 v[168:169], v[112:113], v[156:157]
	v_pk_mul_f32 v[170:171], v[106:107], v[158:159]
	v_pk_mul_f32 v[150:151], v[108:109], v[164:165]
	v_cvt_pk_bf16_f32 v166, v166, v167
	v_cvt_pk_bf16_f32 v167, v168, v169
	v_cvt_pk_bf16_f32 v168, v170, v171
	v_cvt_pk_bf16_f32 v169, v150, v151
	global_store_dwordx4 v238, v[166:169], s[16:17]
	s_waitcnt vmcnt(15)
	v_lshlrev_b32_e32 v154, 16, v192
	v_and_b32_e32 v155, 0xffff0000, v192
	v_lshlrev_b32_e32 v156, 16, v193
	v_and_b32_e32 v157, 0xffff0000, v193
	v_lshlrev_b32_e32 v158, 16, v194
	v_and_b32_e32 v159, 0xffff0000, v194
	v_lshlrev_b32_e32 v164, 16, v195
	v_and_b32_e32 v165, 0xffff0000, v195
	v_pk_mul_f32 v[166:167], v[78:79], v[154:155]
	v_pk_mul_f32 v[168:169], v[80:81], v[156:157]
	v_pk_mul_f32 v[170:171], v[74:75], v[158:159]
	v_pk_mul_f32 v[150:151], v[76:77], v[164:165]
	v_cvt_pk_bf16_f32 v166, v166, v167
	v_cvt_pk_bf16_f32 v167, v168, v169
	v_cvt_pk_bf16_f32 v168, v170, v171
	v_cvt_pk_bf16_f32 v169, v150, v151
	global_store_dwordx4 v238, v[166:169], s[16:17] offset:256
	s_waitcnt vmcnt(15)
	v_lshlrev_b32_e32 v154, 16, v196
	v_and_b32_e32 v155, 0xffff0000, v196
	v_lshlrev_b32_e32 v156, 16, v197
	v_and_b32_e32 v157, 0xffff0000, v197
	v_lshlrev_b32_e32 v158, 16, v198
	v_and_b32_e32 v159, 0xffff0000, v198
	v_lshlrev_b32_e32 v164, 16, v199
	v_and_b32_e32 v165, 0xffff0000, v199
	v_pk_mul_f32 v[166:167], v[102:103], v[154:155]
	v_pk_mul_f32 v[168:169], v[104:105], v[156:157]
	v_pk_mul_f32 v[170:171], v[98:99], v[158:159]
	v_pk_mul_f32 v[150:151], v[100:101], v[164:165]
	v_cvt_pk_bf16_f32 v166, v166, v167
	v_cvt_pk_bf16_f32 v167, v168, v169
	v_cvt_pk_bf16_f32 v168, v170, v171
	v_cvt_pk_bf16_f32 v169, v150, v151
	global_store_dwordx4 v239, v[166:169], s[16:17]
	s_waitcnt vmcnt(15)
	v_lshlrev_b32_e32 v154, 16, v200
	v_and_b32_e32 v155, 0xffff0000, v200
	v_lshlrev_b32_e32 v156, 16, v201
	v_and_b32_e32 v157, 0xffff0000, v201
	v_lshlrev_b32_e32 v158, 16, v202
	v_and_b32_e32 v159, 0xffff0000, v202
	v_lshlrev_b32_e32 v164, 16, v203
	v_and_b32_e32 v165, 0xffff0000, v203
	v_pk_mul_f32 v[166:167], v[70:71], v[154:155]
	v_pk_mul_f32 v[168:169], v[72:73], v[156:157]
	v_pk_mul_f32 v[170:171], v[66:67], v[158:159]
	v_pk_mul_f32 v[150:151], v[68:69], v[164:165]
	v_cvt_pk_bf16_f32 v166, v166, v167
	v_cvt_pk_bf16_f32 v167, v168, v169
	v_cvt_pk_bf16_f32 v168, v170, v171
	v_cvt_pk_bf16_f32 v169, v150, v151
	global_store_dwordx4 v239, v[166:169], s[16:17] offset:256
	s_waitcnt vmcnt(15)
	v_lshlrev_b32_e32 v154, 16, v204
	v_and_b32_e32 v155, 0xffff0000, v204
	v_lshlrev_b32_e32 v156, 16, v205
	v_and_b32_e32 v157, 0xffff0000, v205
	v_lshlrev_b32_e32 v158, 16, v206
	v_and_b32_e32 v159, 0xffff0000, v206
	v_lshlrev_b32_e32 v164, 16, v207
	v_and_b32_e32 v165, 0xffff0000, v207
	v_pk_mul_f32 v[166:167], v[62:63], v[154:155]
	v_pk_mul_f32 v[168:169], v[64:65], v[156:157]
	v_pk_mul_f32 v[170:171], v[58:59], v[158:159]
	v_pk_mul_f32 v[150:151], v[60:61], v[164:165]
	v_cvt_pk_bf16_f32 v166, v166, v167
	v_cvt_pk_bf16_f32 v167, v168, v169
	v_cvt_pk_bf16_f32 v168, v170, v171
	v_cvt_pk_bf16_f32 v169, v150, v151
	global_store_dwordx4 v146, v[166:169], s[16:17]
	s_waitcnt vmcnt(15)
	v_lshlrev_b32_e32 v154, 16, v208
	v_and_b32_e32 v155, 0xffff0000, v208
	v_lshlrev_b32_e32 v156, 16, v209
	v_and_b32_e32 v157, 0xffff0000, v209
	v_lshlrev_b32_e32 v158, 16, v210
	v_and_b32_e32 v159, 0xffff0000, v210
	v_lshlrev_b32_e32 v164, 16, v211
	v_and_b32_e32 v165, 0xffff0000, v211
	v_pk_mul_f32 v[166:167], v[30:31], v[154:155]
	v_pk_mul_f32 v[168:169], v[32:33], v[156:157]
	v_pk_mul_f32 v[170:171], v[26:27], v[158:159]
	v_pk_mul_f32 v[150:151], v[28:29], v[164:165]
	v_cvt_pk_bf16_f32 v166, v166, v167
	v_cvt_pk_bf16_f32 v167, v168, v169
	v_cvt_pk_bf16_f32 v168, v170, v171
	v_cvt_pk_bf16_f32 v169, v150, v151
	global_store_dwordx4 v146, v[166:169], s[16:17] offset:256
	s_waitcnt vmcnt(15)
	v_lshlrev_b32_e32 v154, 16, v212
	v_and_b32_e32 v155, 0xffff0000, v212
	v_lshlrev_b32_e32 v156, 16, v213
	v_and_b32_e32 v157, 0xffff0000, v213
	v_lshlrev_b32_e32 v158, 16, v214
	v_and_b32_e32 v159, 0xffff0000, v214
	v_lshlrev_b32_e32 v164, 16, v215
	v_and_b32_e32 v165, 0xffff0000, v215
	v_pk_mul_f32 v[166:167], v[54:55], v[154:155]
	v_pk_mul_f32 v[168:169], v[56:57], v[156:157]
	v_pk_mul_f32 v[170:171], v[50:51], v[158:159]
	v_pk_mul_f32 v[150:151], v[52:53], v[164:165]
	v_cvt_pk_bf16_f32 v166, v166, v167
	v_cvt_pk_bf16_f32 v167, v168, v169
	v_cvt_pk_bf16_f32 v168, v170, v171
	v_cvt_pk_bf16_f32 v169, v150, v151
	global_store_dwordx4 v147, v[166:169], s[16:17]
	s_waitcnt vmcnt(15)
	v_lshlrev_b32_e32 v154, 16, v216
	v_and_b32_e32 v155, 0xffff0000, v216
	v_lshlrev_b32_e32 v156, 16, v217
	v_and_b32_e32 v157, 0xffff0000, v217
	v_lshlrev_b32_e32 v158, 16, v218
	v_and_b32_e32 v159, 0xffff0000, v218
	v_lshlrev_b32_e32 v164, 16, v219
	v_and_b32_e32 v165, 0xffff0000, v219
	v_pk_mul_f32 v[166:167], v[22:23], v[154:155]
	v_pk_mul_f32 v[168:169], v[24:25], v[156:157]
	v_pk_mul_f32 v[170:171], v[18:19], v[158:159]
	v_pk_mul_f32 v[150:151], v[20:21], v[164:165]
	v_cvt_pk_bf16_f32 v166, v166, v167
	v_cvt_pk_bf16_f32 v167, v168, v169
	v_cvt_pk_bf16_f32 v168, v170, v171
	v_cvt_pk_bf16_f32 v169, v150, v151
	global_store_dwordx4 v147, v[166:169], s[16:17] offset:256
	s_waitcnt vmcnt(15)
	v_lshlrev_b32_e32 v154, 16, v220
	v_and_b32_e32 v155, 0xffff0000, v220
	v_lshlrev_b32_e32 v156, 16, v221
	v_and_b32_e32 v157, 0xffff0000, v221
	v_lshlrev_b32_e32 v158, 16, v222
	v_and_b32_e32 v159, 0xffff0000, v222
	v_lshlrev_b32_e32 v164, 16, v223
	v_and_b32_e32 v165, 0xffff0000, v223
	v_pk_mul_f32 v[166:167], v[46:47], v[154:155]
	v_pk_mul_f32 v[168:169], v[48:49], v[156:157]
	v_pk_mul_f32 v[170:171], v[42:43], v[158:159]
	v_pk_mul_f32 v[150:151], v[44:45], v[164:165]
	v_cvt_pk_bf16_f32 v166, v166, v167
	v_cvt_pk_bf16_f32 v167, v168, v169
	v_cvt_pk_bf16_f32 v168, v170, v171
	v_cvt_pk_bf16_f32 v169, v150, v151
	global_store_dwordx4 v148, v[166:169], s[16:17]
	s_waitcnt vmcnt(15)
	v_lshlrev_b32_e32 v154, 16, v224
	v_and_b32_e32 v155, 0xffff0000, v224
	v_lshlrev_b32_e32 v156, 16, v225
	v_and_b32_e32 v157, 0xffff0000, v225
	v_lshlrev_b32_e32 v158, 16, v226
	v_and_b32_e32 v159, 0xffff0000, v226
	v_lshlrev_b32_e32 v164, 16, v227
	v_and_b32_e32 v165, 0xffff0000, v227
	v_pk_mul_f32 v[166:167], v[14:15], v[154:155]
	v_pk_mul_f32 v[168:169], v[16:17], v[156:157]
	v_pk_mul_f32 v[170:171], v[10:11], v[158:159]
	v_pk_mul_f32 v[150:151], v[12:13], v[164:165]
	v_cvt_pk_bf16_f32 v166, v166, v167
	v_cvt_pk_bf16_f32 v167, v168, v169
	v_cvt_pk_bf16_f32 v168, v170, v171
	v_cvt_pk_bf16_f32 v169, v150, v151
	global_store_dwordx4 v148, v[166:169], s[16:17] offset:256
	s_waitcnt vmcnt(15)
	v_lshlrev_b32_e32 v154, 16, v228
	v_and_b32_e32 v155, 0xffff0000, v228
	v_lshlrev_b32_e32 v156, 16, v229
	v_and_b32_e32 v157, 0xffff0000, v229
	v_lshlrev_b32_e32 v158, 16, v230
	v_and_b32_e32 v159, 0xffff0000, v230
	v_lshlrev_b32_e32 v164, 16, v231
	v_and_b32_e32 v165, 0xffff0000, v231
	v_pk_mul_f32 v[166:167], v[38:39], v[154:155]
	v_pk_mul_f32 v[168:169], v[40:41], v[156:157]
	v_pk_mul_f32 v[170:171], v[34:35], v[158:159]
	v_pk_mul_f32 v[150:151], v[36:37], v[164:165]
	v_cvt_pk_bf16_f32 v166, v166, v167
	v_cvt_pk_bf16_f32 v167, v168, v169
	v_cvt_pk_bf16_f32 v168, v170, v171
	v_cvt_pk_bf16_f32 v169, v150, v151
	global_store_dwordx4 v149, v[166:169], s[16:17]
	s_waitcnt vmcnt(15)
	v_lshlrev_b32_e32 v154, 16, v232
	v_and_b32_e32 v155, 0xffff0000, v232
	v_lshlrev_b32_e32 v156, 16, v233
	v_and_b32_e32 v157, 0xffff0000, v233
	v_lshlrev_b32_e32 v158, 16, v234
	v_and_b32_e32 v159, 0xffff0000, v234
	v_lshlrev_b32_e32 v164, 16, v235
	v_and_b32_e32 v165, 0xffff0000, v235
	v_pk_mul_f32 v[166:167], v[6:7], v[154:155]
	v_pk_mul_f32 v[168:169], v[8:9], v[156:157]
	v_pk_mul_f32 v[170:171], v[2:3], v[158:159]
	v_pk_mul_f32 v[150:151], v[4:5], v[164:165]
	v_cvt_pk_bf16_f32 v166, v166, v167
	v_cvt_pk_bf16_f32 v167, v168, v169
	v_cvt_pk_bf16_f32 v168, v170, v171
	v_cvt_pk_bf16_f32 v169, v150, v151
	global_store_dwordx4 v149, v[166:169], s[16:17] offset:256
	s_mov_b64 s[6:7], 0
	s_branch .Lepi9_done
.Lepi9_keep:
	global_load_dwordx4 v[172:175], v236, s[14:15]
	global_load_dwordx4 v[176:179], v236, s[12:13]
	global_load_dwordx4 v[180:183], v236, s[14:15] offset:256
	global_load_dwordx4 v[184:187], v236, s[12:13] offset:256
	global_load_dwordx4 v[188:191], v237, s[14:15]
	global_load_dwordx4 v[192:195], v237, s[12:13]
	global_load_dwordx4 v[196:199], v237, s[14:15] offset:256
	global_load_dwordx4 v[200:203], v237, s[12:13] offset:256
	global_load_dwordx4 v[204:207], v238, s[14:15]
	global_load_dwordx4 v[208:211], v238, s[12:13]
	global_load_dwordx4 v[212:215], v238, s[14:15] offset:256
	global_load_dwordx4 v[216:219], v238, s[12:13] offset:256
	global_load_dwordx4 v[220:223], v239, s[14:15]
	global_load_dwordx4 v[224:227], v239, s[12:13]
	global_load_dwordx4 v[228:231], v239, s[14:15] offset:256
	global_load_dwordx4 v[232:235], v239, s[12:13] offset:256
	s_waitcnt vmcnt(14)
	v_lshlrev_b32_e32 v154, 16, v172
	v_and_b32_e32 v155, 0xffff0000, v172
	v_lshlrev_b32_e32 v156, 16, v173
	v_and_b32_e32 v157, 0xffff0000, v173
	v_lshlrev_b32_e32 v158, 16, v174
	v_and_b32_e32 v159, 0xffff0000, v174
	v_lshlrev_b32_e32 v164, 16, v175
	v_and_b32_e32 v165, 0xffff0000, v175
	v_max_f32_e32 v154, 0xda24260, v154
	v_max_f32_e32 v155, 0xda24260, v155
	v_max_f32_e32 v156, 0xda24260, v156
	v_max_f32_e32 v157, 0xda24260, v157
	v_max_f32_e32 v158, 0xda24260, v158
	v_max_f32_e32 v159, 0xda24260, v159
	v_max_f32_e32 v164, 0xda24260, v164
	v_max_f32_e32 v165, 0xda24260, v165
	v_rcp_f32_e32 v154, v154
	v_rcp_f32_e32 v155, v155
	v_rcp_f32_e32 v156, v156
	v_rcp_f32_e32 v157, v157
	v_rcp_f32_e32 v158, v158
	v_rcp_f32_e32 v159, v159
	v_rcp_f32_e32 v164, v164
	v_rcp_f32_e32 v165, v165
	v_lshlrev_b32_e32 v166, 16, v176
	v_and_b32_e32 v167, 0xffff0000, v176
	v_lshlrev_b32_e32 v168, 16, v177
	v_and_b32_e32 v169, 0xffff0000, v177
	v_lshlrev_b32_e32 v170, 16, v178
	v_and_b32_e32 v171, 0xffff0000, v178
	v_lshlrev_b32_e32 v150, 16, v179
	v_and_b32_e32 v151, 0xffff0000, v179
	v_pk_mul_f32 v[154:155], v[154:155], v[166:167]
	v_pk_mul_f32 v[156:157], v[156:157], v[168:169]
	v_pk_mul_f32 v[158:159], v[158:159], v[170:171]
	v_pk_mul_f32 v[164:165], v[164:165], v[150:151]
	v_pk_mul_f32 v[126:127], v[126:127], v[154:155]
	v_pk_mul_f32 v[128:129], v[128:129], v[156:157]
	v_pk_mul_f32 v[122:123], v[122:123], v[158:159]
	v_pk_mul_f32 v[124:125], v[124:125], v[164:165]
	global_load_dwordx4 v[172:175], v146, s[14:15]
	global_load_dwordx4 v[176:179], v146, s[12:13]
	s_waitcnt vmcnt(14)
	v_lshlrev_b32_e32 v154, 16, v180
	v_and_b32_e32 v155, 0xffff0000, v180
	v_lshlrev_b32_e32 v156, 16, v181
	v_and_b32_e32 v157, 0xffff0000, v181
	v_lshlrev_b32_e32 v158, 16, v182
	v_and_b32_e32 v159, 0xffff0000, v182
	v_lshlrev_b32_e32 v164, 16, v183
	v_and_b32_e32 v165, 0xffff0000, v183
	v_max_f32_e32 v154, 0xda24260, v154
	v_max_f32_e32 v155, 0xda24260, v155
	v_max_f32_e32 v156, 0xda24260, v156
	v_max_f32_e32 v157, 0xda24260, v157
	v_max_f32_e32 v158, 0xda24260, v158
	v_max_f32_e32 v159, 0xda24260, v159
	v_max_f32_e32 v164, 0xda24260, v164
	v_max_f32_e32 v165, 0xda24260, v165
	v_rcp_f32_e32 v154, v154
	v_rcp_f32_e32 v155, v155
	v_rcp_f32_e32 v156, v156
	v_rcp_f32_e32 v157, v157
	v_rcp_f32_e32 v158, v158
	v_rcp_f32_e32 v159, v159
	v_rcp_f32_e32 v164, v164
	v_rcp_f32_e32 v165, v165
	v_lshlrev_b32_e32 v166, 16, v184
	v_and_b32_e32 v167, 0xffff0000, v184
	v_lshlrev_b32_e32 v168, 16, v185
	v_and_b32_e32 v169, 0xffff0000, v185
	v_lshlrev_b32_e32 v170, 16, v186
	v_and_b32_e32 v171, 0xffff0000, v186
	v_lshlrev_b32_e32 v150, 16, v187
	v_and_b32_e32 v151, 0xffff0000, v187
	v_pk_mul_f32 v[154:155], v[154:155], v[166:167]
	v_pk_mul_f32 v[156:157], v[156:157], v[168:169]
	v_pk_mul_f32 v[158:159], v[158:159], v[170:171]
	v_pk_mul_f32 v[164:165], v[164:165], v[150:151]
	v_pk_mul_f32 v[94:95], v[94:95], v[154:155]
	v_pk_mul_f32 v[96:97], v[96:97], v[156:157]
	v_pk_mul_f32 v[90:91], v[90:91], v[158:159]
	v_pk_mul_f32 v[92:93], v[92:93], v[164:165]
	global_load_dwordx4 v[180:183], v146, s[14:15] offset:256
	global_load_dwordx4 v[184:187], v146, s[12:13] offset:256
	s_waitcnt vmcnt(14)
	v_lshlrev_b32_e32 v154, 16, v188
	v_and_b32_e32 v155, 0xffff0000, v188
	v_lshlrev_b32_e32 v156, 16, v189
	v_and_b32_e32 v157, 0xffff0000, v189
	v_lshlrev_b32_e32 v158, 16, v190
	v_and_b32_e32 v159, 0xffff0000, v190
	v_lshlrev_b32_e32 v164, 16, v191
	v_and_b32_e32 v165, 0xffff0000, v191
	v_max_f32_e32 v154, 0xda24260, v154
	v_max_f32_e32 v155, 0xda24260, v155
	v_max_f32_e32 v156, 0xda24260, v156
	v_max_f32_e32 v157, 0xda24260, v157
	v_max_f32_e32 v158, 0xda24260, v158
	v_max_f32_e32 v159, 0xda24260, v159
	v_max_f32_e32 v164, 0xda24260, v164
	v_max_f32_e32 v165, 0xda24260, v165
	v_rcp_f32_e32 v154, v154
	v_rcp_f32_e32 v155, v155
	v_rcp_f32_e32 v156, v156
	v_rcp_f32_e32 v157, v157
	v_rcp_f32_e32 v158, v158
	v_rcp_f32_e32 v159, v159
	v_rcp_f32_e32 v164, v164
	v_rcp_f32_e32 v165, v165
	v_lshlrev_b32_e32 v166, 16, v192
	v_and_b32_e32 v167, 0xffff0000, v192
	v_lshlrev_b32_e32 v168, 16, v193
	v_and_b32_e32 v169, 0xffff0000, v193
	v_lshlrev_b32_e32 v170, 16, v194
	v_and_b32_e32 v171, 0xffff0000, v194
	v_lshlrev_b32_e32 v150, 16, v195
	v_and_b32_e32 v151, 0xffff0000, v195
	v_pk_mul_f32 v[154:155], v[154:155], v[166:167]
	v_pk_mul_f32 v[156:157], v[156:157], v[168:169]
	v_pk_mul_f32 v[158:159], v[158:159], v[170:171]
	v_pk_mul_f32 v[164:165], v[164:165], v[150:151]
	v_pk_mul_f32 v[118:119], v[118:119], v[154:155]
	v_pk_mul_f32 v[120:121], v[120:121], v[156:157]
	v_pk_mul_f32 v[114:115], v[114:115], v[158:159]
	v_pk_mul_f32 v[116:117], v[116:117], v[164:165]
	global_load_dwordx4 v[188:191], v147, s[14:15]
	global_load_dwordx4 v[192:195], v147, s[12:13]
	s_waitcnt vmcnt(14)
	v_lshlrev_b32_e32 v154, 16, v196
	v_and_b32_e32 v155, 0xffff0000, v196
	v_lshlrev_b32_e32 v156, 16, v197
	v_and_b32_e32 v157, 0xffff0000, v197
	v_lshlrev_b32_e32 v158, 16, v198
	v_and_b32_e32 v159, 0xffff0000, v198
	v_lshlrev_b32_e32 v164, 16, v199
	v_and_b32_e32 v165, 0xffff0000, v199
	v_max_f32_e32 v154, 0xda24260, v154
	v_max_f32_e32 v155, 0xda24260, v155
	v_max_f32_e32 v156, 0xda24260, v156
	v_max_f32_e32 v157, 0xda24260, v157
	v_max_f32_e32 v158, 0xda24260, v158
	v_max_f32_e32 v159, 0xda24260, v159
	v_max_f32_e32 v164, 0xda24260, v164
	v_max_f32_e32 v165, 0xda24260, v165
	v_rcp_f32_e32 v154, v154
	v_rcp_f32_e32 v155, v155
	v_rcp_f32_e32 v156, v156
	v_rcp_f32_e32 v157, v157
	v_rcp_f32_e32 v158, v158
	v_rcp_f32_e32 v159, v159
	v_rcp_f32_e32 v164, v164
	v_rcp_f32_e32 v165, v165
	v_lshlrev_b32_e32 v166, 16, v200
	v_and_b32_e32 v167, 0xffff0000, v200
	v_lshlrev_b32_e32 v168, 16, v201
	v_and_b32_e32 v169, 0xffff0000, v201
	v_lshlrev_b32_e32 v170, 16, v202
	v_and_b32_e32 v171, 0xffff0000, v202
	v_lshlrev_b32_e32 v150, 16, v203
	v_and_b32_e32 v151, 0xffff0000, v203
	v_pk_mul_f32 v[154:155], v[154:155], v[166:167]
	v_pk_mul_f32 v[156:157], v[156:157], v[168:169]
	v_pk_mul_f32 v[158:159], v[158:159], v[170:171]
	v_pk_mul_f32 v[164:165], v[164:165], v[150:151]
	v_pk_mul_f32 v[86:87], v[86:87], v[154:155]
	v_pk_mul_f32 v[88:89], v[88:89], v[156:157]
	v_pk_mul_f32 v[82:83], v[82:83], v[158:159]
	v_pk_mul_f32 v[84:85], v[84:85], v[164:165]
	global_load_dwordx4 v[196:199], v147, s[14:15] offset:256
	global_load_dwordx4 v[200:203], v147, s[12:13] offset:256
	s_waitcnt vmcnt(14)
	v_lshlrev_b32_e32 v154, 16, v204
	v_and_b32_e32 v155, 0xffff0000, v204
	v_lshlrev_b32_e32 v156, 16, v205
	v_and_b32_e32 v157, 0xffff0000, v205
	v_lshlrev_b32_e32 v158, 16, v206
	v_and_b32_e32 v159, 0xffff0000, v206
	v_lshlrev_b32_e32 v164, 16, v207
	v_and_b32_e32 v165, 0xffff0000, v207
	v_max_f32_e32 v154, 0xda24260, v154
	v_max_f32_e32 v155, 0xda24260, v155
	v_max_f32_e32 v156, 0xda24260, v156
	v_max_f32_e32 v157, 0xda24260, v157
	v_max_f32_e32 v158, 0xda24260, v158
	v_max_f32_e32 v159, 0xda24260, v159
	v_max_f32_e32 v164, 0xda24260, v164
	v_max_f32_e32 v165, 0xda24260, v165
	v_rcp_f32_e32 v154, v154
	v_rcp_f32_e32 v155, v155
	v_rcp_f32_e32 v156, v156
	v_rcp_f32_e32 v157, v157
	v_rcp_f32_e32 v158, v158
	v_rcp_f32_e32 v159, v159
	v_rcp_f32_e32 v164, v164
	v_rcp_f32_e32 v165, v165
	v_lshlrev_b32_e32 v166, 16, v208
	v_and_b32_e32 v167, 0xffff0000, v208
	v_lshlrev_b32_e32 v168, 16, v209
	v_and_b32_e32 v169, 0xffff0000, v209
	v_lshlrev_b32_e32 v170, 16, v210
	v_and_b32_e32 v171, 0xffff0000, v210
	v_lshlrev_b32_e32 v150, 16, v211
	v_and_b32_e32 v151, 0xffff0000, v211
	v_pk_mul_f32 v[154:155], v[154:155], v[166:167]
	v_pk_mul_f32 v[156:157], v[156:157], v[168:169]
	v_pk_mul_f32 v[158:159], v[158:159], v[170:171]
	v_pk_mul_f32 v[164:165], v[164:165], v[150:151]
	v_pk_mul_f32 v[110:111], v[110:111], v[154:155]
	v_pk_mul_f32 v[112:113], v[112:113], v[156:157]
	v_pk_mul_f32 v[106:107], v[106:107], v[158:159]
	v_pk_mul_f32 v[108:109], v[108:109], v[164:165]
	global_load_dwordx4 v[204:207], v148, s[14:15]
	global_load_dwordx4 v[208:211], v148, s[12:13]
	s_waitcnt vmcnt(14)
	v_lshlrev_b32_e32 v154, 16, v212
	v_and_b32_e32 v155, 0xffff0000, v212
	v_lshlrev_b32_e32 v156, 16, v213
	v_and_b32_e32 v157, 0xffff0000, v213
	v_lshlrev_b32_e32 v158, 16, v214
	v_and_b32_e32 v159, 0xffff0000, v214
	v_lshlrev_b32_e32 v164, 16, v215
	v_and_b32_e32 v165, 0xffff0000, v215
	v_max_f32_e32 v154, 0xda24260, v154
	v_max_f32_e32 v155, 0xda24260, v155
	v_max_f32_e32 v156, 0xda24260, v156
	v_max_f32_e32 v157, 0xda24260, v157
	v_max_f32_e32 v158, 0xda24260, v158
	v_max_f32_e32 v159, 0xda24260, v159
	v_max_f32_e32 v164, 0xda24260, v164
	v_max_f32_e32 v165, 0xda24260, v165
	v_rcp_f32_e32 v154, v154
	v_rcp_f32_e32 v155, v155
	v_rcp_f32_e32 v156, v156
	v_rcp_f32_e32 v157, v157
	v_rcp_f32_e32 v158, v158
	v_rcp_f32_e32 v159, v159
	v_rcp_f32_e32 v164, v164
	v_rcp_f32_e32 v165, v165
	v_lshlrev_b32_e32 v166, 16, v216
	v_and_b32_e32 v167, 0xffff0000, v216
	v_lshlrev_b32_e32 v168, 16, v217
	v_and_b32_e32 v169, 0xffff0000, v217
	v_lshlrev_b32_e32 v170, 16, v218
	v_and_b32_e32 v171, 0xffff0000, v218
	v_lshlrev_b32_e32 v150, 16, v219
	v_and_b32_e32 v151, 0xffff0000, v219
	v_pk_mul_f32 v[154:155], v[154:155], v[166:167]
	v_pk_mul_f32 v[156:157], v[156:157], v[168:169]
	v_pk_mul_f32 v[158:159], v[158:159], v[170:171]
	v_pk_mul_f32 v[164:165], v[164:165], v[150:151]
	v_pk_mul_f32 v[78:79], v[78:79], v[154:155]
	v_pk_mul_f32 v[80:81], v[80:81], v[156:157]
	v_pk_mul_f32 v[74:75], v[74:75], v[158:159]
	v_pk_mul_f32 v[76:77], v[76:77], v[164:165]
	global_load_dwordx4 v[212:215], v148, s[14:15] offset:256
	global_load_dwordx4 v[216:219], v148, s[12:13] offset:256
	s_waitcnt vmcnt(14)
	v_lshlrev_b32_e32 v154, 16, v220
	v_and_b32_e32 v155, 0xffff0000, v220
	v_lshlrev_b32_e32 v156, 16, v221
	v_and_b32_e32 v157, 0xffff0000, v221
	v_lshlrev_b32_e32 v158, 16, v222
	v_and_b32_e32 v159, 0xffff0000, v222
	v_lshlrev_b32_e32 v164, 16, v223
	v_and_b32_e32 v165, 0xffff0000, v223
	v_max_f32_e32 v154, 0xda24260, v154
	v_max_f32_e32 v155, 0xda24260, v155
	v_max_f32_e32 v156, 0xda24260, v156
	v_max_f32_e32 v157, 0xda24260, v157
	v_max_f32_e32 v158, 0xda24260, v158
	v_max_f32_e32 v159, 0xda24260, v159
	v_max_f32_e32 v164, 0xda24260, v164
	v_max_f32_e32 v165, 0xda24260, v165
	v_rcp_f32_e32 v154, v154
	v_rcp_f32_e32 v155, v155
	v_rcp_f32_e32 v156, v156
	v_rcp_f32_e32 v157, v157
	v_rcp_f32_e32 v158, v158
	v_rcp_f32_e32 v159, v159
	v_rcp_f32_e32 v164, v164
	v_rcp_f32_e32 v165, v165
	v_lshlrev_b32_e32 v166, 16, v224
	v_and_b32_e32 v167, 0xffff0000, v224
	v_lshlrev_b32_e32 v168, 16, v225
	v_and_b32_e32 v169, 0xffff0000, v225
	v_lshlrev_b32_e32 v170, 16, v226
	v_and_b32_e32 v171, 0xffff0000, v226
	v_lshlrev_b32_e32 v150, 16, v227
	v_and_b32_e32 v151, 0xffff0000, v227
	v_pk_mul_f32 v[154:155], v[154:155], v[166:167]
	v_pk_mul_f32 v[156:157], v[156:157], v[168:169]
	v_pk_mul_f32 v[158:159], v[158:159], v[170:171]
	v_pk_mul_f32 v[164:165], v[164:165], v[150:151]
	v_pk_mul_f32 v[102:103], v[102:103], v[154:155]
	v_pk_mul_f32 v[104:105], v[104:105], v[156:157]
	v_pk_mul_f32 v[98:99], v[98:99], v[158:159]
	v_pk_mul_f32 v[100:101], v[100:101], v[164:165]
	global_load_dwordx4 v[220:223], v149, s[14:15]
	global_load_dwordx4 v[224:227], v149, s[12:13]
	s_waitcnt vmcnt(14)
	v_lshlrev_b32_e32 v154, 16, v228
	v_and_b32_e32 v155, 0xffff0000, v228
	v_lshlrev_b32_e32 v156, 16, v229
	v_and_b32_e32 v157, 0xffff0000, v229
	v_lshlrev_b32_e32 v158, 16, v230
	v_and_b32_e32 v159, 0xffff0000, v230
	v_lshlrev_b32_e32 v164, 16, v231
	v_and_b32_e32 v165, 0xffff0000, v231
	v_max_f32_e32 v154, 0xda24260, v154
	v_max_f32_e32 v155, 0xda24260, v155
	v_max_f32_e32 v156, 0xda24260, v156
	v_max_f32_e32 v157, 0xda24260, v157
	v_max_f32_e32 v158, 0xda24260, v158
	v_max_f32_e32 v159, 0xda24260, v159
	v_max_f32_e32 v164, 0xda24260, v164
	v_max_f32_e32 v165, 0xda24260, v165
	v_rcp_f32_e32 v154, v154
	v_rcp_f32_e32 v155, v155
	v_rcp_f32_e32 v156, v156
	v_rcp_f32_e32 v157, v157
	v_rcp_f32_e32 v158, v158
	v_rcp_f32_e32 v159, v159
	v_rcp_f32_e32 v164, v164
	v_rcp_f32_e32 v165, v165
	v_lshlrev_b32_e32 v166, 16, v232
	v_and_b32_e32 v167, 0xffff0000, v232
	v_lshlrev_b32_e32 v168, 16, v233
	v_and_b32_e32 v169, 0xffff0000, v233
	v_lshlrev_b32_e32 v170, 16, v234
	v_and_b32_e32 v171, 0xffff0000, v234
	v_lshlrev_b32_e32 v150, 16, v235
	v_and_b32_e32 v151, 0xffff0000, v235
	v_pk_mul_f32 v[154:155], v[154:155], v[166:167]
	v_pk_mul_f32 v[156:157], v[156:157], v[168:169]
	v_pk_mul_f32 v[158:159], v[158:159], v[170:171]
	v_pk_mul_f32 v[164:165], v[164:165], v[150:151]
	v_pk_mul_f32 v[70:71], v[70:71], v[154:155]
	v_pk_mul_f32 v[72:73], v[72:73], v[156:157]
	v_pk_mul_f32 v[66:67], v[66:67], v[158:159]
	v_pk_mul_f32 v[68:69], v[68:69], v[164:165]
	global_load_dwordx4 v[228:231], v149, s[14:15] offset:256
	global_load_dwordx4 v[232:235], v149, s[12:13] offset:256
	s_waitcnt vmcnt(14)
	v_lshlrev_b32_e32 v154, 16, v172
	v_and_b32_e32 v155, 0xffff0000, v172
	v_lshlrev_b32_e32 v156, 16, v173
	v_and_b32_e32 v157, 0xffff0000, v173
	v_lshlrev_b32_e32 v158, 16, v174
	v_and_b32_e32 v159, 0xffff0000, v174
	v_lshlrev_b32_e32 v164, 16, v175
	v_and_b32_e32 v165, 0xffff0000, v175
	v_max_f32_e32 v154, 0xda24260, v154
	v_max_f32_e32 v155, 0xda24260, v155
	v_max_f32_e32 v156, 0xda24260, v156
	v_max_f32_e32 v157, 0xda24260, v157
	v_max_f32_e32 v158, 0xda24260, v158
	v_max_f32_e32 v159, 0xda24260, v159
	v_max_f32_e32 v164, 0xda24260, v164
	v_max_f32_e32 v165, 0xda24260, v165
	v_rcp_f32_e32 v154, v154
	v_rcp_f32_e32 v155, v155
	v_rcp_f32_e32 v156, v156
	v_rcp_f32_e32 v157, v157
	v_rcp_f32_e32 v158, v158
	v_rcp_f32_e32 v159, v159
	v_rcp_f32_e32 v164, v164
	v_rcp_f32_e32 v165, v165
	v_lshlrev_b32_e32 v166, 16, v176
	v_and_b32_e32 v167, 0xffff0000, v176
	v_lshlrev_b32_e32 v168, 16, v177
	v_and_b32_e32 v169, 0xffff0000, v177
	v_lshlrev_b32_e32 v170, 16, v178
	v_and_b32_e32 v171, 0xffff0000, v178
	v_lshlrev_b32_e32 v150, 16, v179
	v_and_b32_e32 v151, 0xffff0000, v179
	v_pk_mul_f32 v[154:155], v[154:155], v[166:167]
	v_pk_mul_f32 v[156:157], v[156:157], v[168:169]
	v_pk_mul_f32 v[158:159], v[158:159], v[170:171]
	v_pk_mul_f32 v[164:165], v[164:165], v[150:151]
	v_pk_mul_f32 v[62:63], v[62:63], v[154:155]
	v_pk_mul_f32 v[64:65], v[64:65], v[156:157]
	v_pk_mul_f32 v[58:59], v[58:59], v[158:159]
	v_pk_mul_f32 v[60:61], v[60:61], v[164:165]
	s_waitcnt vmcnt(12)
	v_lshlrev_b32_e32 v154, 16, v180
	v_and_b32_e32 v155, 0xffff0000, v180
	v_lshlrev_b32_e32 v156, 16, v181
	v_and_b32_e32 v157, 0xffff0000, v181
	v_lshlrev_b32_e32 v158, 16, v182
	v_and_b32_e32 v159, 0xffff0000, v182
	v_lshlrev_b32_e32 v164, 16, v183
	v_and_b32_e32 v165, 0xffff0000, v183
	v_max_f32_e32 v154, 0xda24260, v154
	v_max_f32_e32 v155, 0xda24260, v155
	v_max_f32_e32 v156, 0xda24260, v156
	v_max_f32_e32 v157, 0xda24260, v157
	v_max_f32_e32 v158, 0xda24260, v158
	v_max_f32_e32 v159, 0xda24260, v159
	v_max_f32_e32 v164, 0xda24260, v164
	v_max_f32_e32 v165, 0xda24260, v165
	v_rcp_f32_e32 v154, v154
	v_rcp_f32_e32 v155, v155
	v_rcp_f32_e32 v156, v156
	v_rcp_f32_e32 v157, v157
	v_rcp_f32_e32 v158, v158
	v_rcp_f32_e32 v159, v159
	v_rcp_f32_e32 v164, v164
	v_rcp_f32_e32 v165, v165
	v_lshlrev_b32_e32 v166, 16, v184
	v_and_b32_e32 v167, 0xffff0000, v184
	v_lshlrev_b32_e32 v168, 16, v185
	v_and_b32_e32 v169, 0xffff0000, v185
	v_lshlrev_b32_e32 v170, 16, v186
	v_and_b32_e32 v171, 0xffff0000, v186
	v_lshlrev_b32_e32 v150, 16, v187
	v_and_b32_e32 v151, 0xffff0000, v187
	v_pk_mul_f32 v[154:155], v[154:155], v[166:167]
	v_pk_mul_f32 v[156:157], v[156:157], v[168:169]
	v_pk_mul_f32 v[158:159], v[158:159], v[170:171]
	v_pk_mul_f32 v[164:165], v[164:165], v[150:151]
	v_pk_mul_f32 v[30:31], v[30:31], v[154:155]
	v_pk_mul_f32 v[32:33], v[32:33], v[156:157]
	v_pk_mul_f32 v[26:27], v[26:27], v[158:159]
	v_pk_mul_f32 v[28:29], v[28:29], v[164:165]
	s_waitcnt vmcnt(10)
	v_lshlrev_b32_e32 v154, 16, v188
	v_and_b32_e32 v155, 0xffff0000, v188
	v_lshlrev_b32_e32 v156, 16, v189
	v_and_b32_e32 v157, 0xffff0000, v189
	v_lshlrev_b32_e32 v158, 16, v190
	v_and_b32_e32 v159, 0xffff0000, v190
	v_lshlrev_b32_e32 v164, 16, v191
	v_and_b32_e32 v165, 0xffff0000, v191
	v_max_f32_e32 v154, 0xda24260, v154
	v_max_f32_e32 v155, 0xda24260, v155
	v_max_f32_e32 v156, 0xda24260, v156
	v_max_f32_e32 v157, 0xda24260, v157
	v_max_f32_e32 v158, 0xda24260, v158
	v_max_f32_e32 v159, 0xda24260, v159
	v_max_f32_e32 v164, 0xda24260, v164
	v_max_f32_e32 v165, 0xda24260, v165
	v_rcp_f32_e32 v154, v154
	v_rcp_f32_e32 v155, v155
	v_rcp_f32_e32 v156, v156
	v_rcp_f32_e32 v157, v157
	v_rcp_f32_e32 v158, v158
	v_rcp_f32_e32 v159, v159
	v_rcp_f32_e32 v164, v164
	v_rcp_f32_e32 v165, v165
	v_lshlrev_b32_e32 v166, 16, v192
	v_and_b32_e32 v167, 0xffff0000, v192
	v_lshlrev_b32_e32 v168, 16, v193
	v_and_b32_e32 v169, 0xffff0000, v193
	v_lshlrev_b32_e32 v170, 16, v194
	v_and_b32_e32 v171, 0xffff0000, v194
	v_lshlrev_b32_e32 v150, 16, v195
	v_and_b32_e32 v151, 0xffff0000, v195
	v_pk_mul_f32 v[154:155], v[154:155], v[166:167]
	v_pk_mul_f32 v[156:157], v[156:157], v[168:169]
	v_pk_mul_f32 v[158:159], v[158:159], v[170:171]
	v_pk_mul_f32 v[164:165], v[164:165], v[150:151]
	v_pk_mul_f32 v[54:55], v[54:55], v[154:155]
	v_pk_mul_f32 v[56:57], v[56:57], v[156:157]
	v_pk_mul_f32 v[50:51], v[50:51], v[158:159]
	v_pk_mul_f32 v[52:53], v[52:53], v[164:165]
	s_waitcnt vmcnt(8)
	v_lshlrev_b32_e32 v154, 16, v196
	v_and_b32_e32 v155, 0xffff0000, v196
	v_lshlrev_b32_e32 v156, 16, v197
	v_and_b32_e32 v157, 0xffff0000, v197
	v_lshlrev_b32_e32 v158, 16, v198
	v_and_b32_e32 v159, 0xffff0000, v198
	v_lshlrev_b32_e32 v164, 16, v199
	v_and_b32_e32 v165, 0xffff0000, v199
	v_max_f32_e32 v154, 0xda24260, v154
	v_max_f32_e32 v155, 0xda24260, v155
	v_max_f32_e32 v156, 0xda24260, v156
	v_max_f32_e32 v157, 0xda24260, v157
	v_max_f32_e32 v158, 0xda24260, v158
	v_max_f32_e32 v159, 0xda24260, v159
	v_max_f32_e32 v164, 0xda24260, v164
	v_max_f32_e32 v165, 0xda24260, v165
	v_rcp_f32_e32 v154, v154
	v_rcp_f32_e32 v155, v155
	v_rcp_f32_e32 v156, v156
	v_rcp_f32_e32 v157, v157
	v_rcp_f32_e32 v158, v158
	v_rcp_f32_e32 v159, v159
	v_rcp_f32_e32 v164, v164
	v_rcp_f32_e32 v165, v165
	v_lshlrev_b32_e32 v166, 16, v200
	v_and_b32_e32 v167, 0xffff0000, v200
	v_lshlrev_b32_e32 v168, 16, v201
	v_and_b32_e32 v169, 0xffff0000, v201
	v_lshlrev_b32_e32 v170, 16, v202
	v_and_b32_e32 v171, 0xffff0000, v202
	v_lshlrev_b32_e32 v150, 16, v203
	v_and_b32_e32 v151, 0xffff0000, v203
	v_pk_mul_f32 v[154:155], v[154:155], v[166:167]
	v_pk_mul_f32 v[156:157], v[156:157], v[168:169]
	v_pk_mul_f32 v[158:159], v[158:159], v[170:171]
	v_pk_mul_f32 v[164:165], v[164:165], v[150:151]
	v_pk_mul_f32 v[22:23], v[22:23], v[154:155]
	v_pk_mul_f32 v[24:25], v[24:25], v[156:157]
	v_pk_mul_f32 v[18:19], v[18:19], v[158:159]
	v_pk_mul_f32 v[20:21], v[20:21], v[164:165]
	s_waitcnt vmcnt(6)
	v_lshlrev_b32_e32 v154, 16, v204
	v_and_b32_e32 v155, 0xffff0000, v204
	v_lshlrev_b32_e32 v156, 16, v205
	v_and_b32_e32 v157, 0xffff0000, v205
	v_lshlrev_b32_e32 v158, 16, v206
	v_and_b32_e32 v159, 0xffff0000, v206
	v_lshlrev_b32_e32 v164, 16, v207
	v_and_b32_e32 v165, 0xffff0000, v207
	v_max_f32_e32 v154, 0xda24260, v154
	v_max_f32_e32 v155, 0xda24260, v155
	v_max_f32_e32 v156, 0xda24260, v156
	v_max_f32_e32 v157, 0xda24260, v157
	v_max_f32_e32 v158, 0xda24260, v158
	v_max_f32_e32 v159, 0xda24260, v159
	v_max_f32_e32 v164, 0xda24260, v164
	v_max_f32_e32 v165, 0xda24260, v165
	v_rcp_f32_e32 v154, v154
	v_rcp_f32_e32 v155, v155
	v_rcp_f32_e32 v156, v156
	v_rcp_f32_e32 v157, v157
	v_rcp_f32_e32 v158, v158
	v_rcp_f32_e32 v159, v159
	v_rcp_f32_e32 v164, v164
	v_rcp_f32_e32 v165, v165
	v_lshlrev_b32_e32 v166, 16, v208
	v_and_b32_e32 v167, 0xffff0000, v208
	v_lshlrev_b32_e32 v168, 16, v209
	v_and_b32_e32 v169, 0xffff0000, v209
	v_lshlrev_b32_e32 v170, 16, v210
	v_and_b32_e32 v171, 0xffff0000, v210
	v_lshlrev_b32_e32 v150, 16, v211
	v_and_b32_e32 v151, 0xffff0000, v211
	v_pk_mul_f32 v[154:155], v[154:155], v[166:167]
	v_pk_mul_f32 v[156:157], v[156:157], v[168:169]
	v_pk_mul_f32 v[158:159], v[158:159], v[170:171]
	v_pk_mul_f32 v[164:165], v[164:165], v[150:151]
	v_pk_mul_f32 v[46:47], v[46:47], v[154:155]
	v_pk_mul_f32 v[48:49], v[48:49], v[156:157]
	v_pk_mul_f32 v[42:43], v[42:43], v[158:159]
	v_pk_mul_f32 v[44:45], v[44:45], v[164:165]
	s_waitcnt vmcnt(4)
	v_lshlrev_b32_e32 v154, 16, v212
	v_and_b32_e32 v155, 0xffff0000, v212
	v_lshlrev_b32_e32 v156, 16, v213
	v_and_b32_e32 v157, 0xffff0000, v213
	v_lshlrev_b32_e32 v158, 16, v214
	v_and_b32_e32 v159, 0xffff0000, v214
	v_lshlrev_b32_e32 v164, 16, v215
	v_and_b32_e32 v165, 0xffff0000, v215
	v_max_f32_e32 v154, 0xda24260, v154
	v_max_f32_e32 v155, 0xda24260, v155
	v_max_f32_e32 v156, 0xda24260, v156
	v_max_f32_e32 v157, 0xda24260, v157
	v_max_f32_e32 v158, 0xda24260, v158
	v_max_f32_e32 v159, 0xda24260, v159
	v_max_f32_e32 v164, 0xda24260, v164
	v_max_f32_e32 v165, 0xda24260, v165
	v_rcp_f32_e32 v154, v154
	v_rcp_f32_e32 v155, v155
	v_rcp_f32_e32 v156, v156
	v_rcp_f32_e32 v157, v157
	v_rcp_f32_e32 v158, v158
	v_rcp_f32_e32 v159, v159
	v_rcp_f32_e32 v164, v164
	v_rcp_f32_e32 v165, v165
	v_lshlrev_b32_e32 v166, 16, v216
	v_and_b32_e32 v167, 0xffff0000, v216
	v_lshlrev_b32_e32 v168, 16, v217
	v_and_b32_e32 v169, 0xffff0000, v217
	v_lshlrev_b32_e32 v170, 16, v218
	v_and_b32_e32 v171, 0xffff0000, v218
	v_lshlrev_b32_e32 v150, 16, v219
	v_and_b32_e32 v151, 0xffff0000, v219
	v_pk_mul_f32 v[154:155], v[154:155], v[166:167]
	v_pk_mul_f32 v[156:157], v[156:157], v[168:169]
	v_pk_mul_f32 v[158:159], v[158:159], v[170:171]
	v_pk_mul_f32 v[164:165], v[164:165], v[150:151]
	v_pk_mul_f32 v[14:15], v[14:15], v[154:155]
	v_pk_mul_f32 v[16:17], v[16:17], v[156:157]
	v_pk_mul_f32 v[10:11], v[10:11], v[158:159]
	v_pk_mul_f32 v[12:13], v[12:13], v[164:165]
	s_waitcnt vmcnt(2)
	v_lshlrev_b32_e32 v154, 16, v220
	v_and_b32_e32 v155, 0xffff0000, v220
	v_lshlrev_b32_e32 v156, 16, v221
	v_and_b32_e32 v157, 0xffff0000, v221
	v_lshlrev_b32_e32 v158, 16, v222
	v_and_b32_e32 v159, 0xffff0000, v222
	v_lshlrev_b32_e32 v164, 16, v223
	v_and_b32_e32 v165, 0xffff0000, v223
	v_max_f32_e32 v154, 0xda24260, v154
	v_max_f32_e32 v155, 0xda24260, v155
	v_max_f32_e32 v156, 0xda24260, v156
	v_max_f32_e32 v157, 0xda24260, v157
	v_max_f32_e32 v158, 0xda24260, v158
	v_max_f32_e32 v159, 0xda24260, v159
	v_max_f32_e32 v164, 0xda24260, v164
	v_max_f32_e32 v165, 0xda24260, v165
	v_rcp_f32_e32 v154, v154
	v_rcp_f32_e32 v155, v155
	v_rcp_f32_e32 v156, v156
	v_rcp_f32_e32 v157, v157
	v_rcp_f32_e32 v158, v158
	v_rcp_f32_e32 v159, v159
	v_rcp_f32_e32 v164, v164
	v_rcp_f32_e32 v165, v165
	v_lshlrev_b32_e32 v166, 16, v224
	v_and_b32_e32 v167, 0xffff0000, v224
	v_lshlrev_b32_e32 v168, 16, v225
	v_and_b32_e32 v169, 0xffff0000, v225
	v_lshlrev_b32_e32 v170, 16, v226
	v_and_b32_e32 v171, 0xffff0000, v226
	v_lshlrev_b32_e32 v150, 16, v227
	v_and_b32_e32 v151, 0xffff0000, v227
	v_pk_mul_f32 v[154:155], v[154:155], v[166:167]
	v_pk_mul_f32 v[156:157], v[156:157], v[168:169]
	v_pk_mul_f32 v[158:159], v[158:159], v[170:171]
	v_pk_mul_f32 v[164:165], v[164:165], v[150:151]
	v_pk_mul_f32 v[38:39], v[38:39], v[154:155]
	v_pk_mul_f32 v[40:41], v[40:41], v[156:157]
	v_pk_mul_f32 v[34:35], v[34:35], v[158:159]
	v_pk_mul_f32 v[36:37], v[36:37], v[164:165]
	s_waitcnt vmcnt(0)
	v_lshlrev_b32_e32 v154, 16, v228
	v_and_b32_e32 v155, 0xffff0000, v228
	v_lshlrev_b32_e32 v156, 16, v229
	v_and_b32_e32 v157, 0xffff0000, v229
	v_lshlrev_b32_e32 v158, 16, v230
	v_and_b32_e32 v159, 0xffff0000, v230
	v_lshlrev_b32_e32 v164, 16, v231
	v_and_b32_e32 v165, 0xffff0000, v231
	v_max_f32_e32 v154, 0xda24260, v154
	v_max_f32_e32 v155, 0xda24260, v155
	v_max_f32_e32 v156, 0xda24260, v156
	v_max_f32_e32 v157, 0xda24260, v157
	v_max_f32_e32 v158, 0xda24260, v158
	v_max_f32_e32 v159, 0xda24260, v159
	v_max_f32_e32 v164, 0xda24260, v164
	v_max_f32_e32 v165, 0xda24260, v165
	v_rcp_f32_e32 v154, v154
	v_rcp_f32_e32 v155, v155
	v_rcp_f32_e32 v156, v156
	v_rcp_f32_e32 v157, v157
	v_rcp_f32_e32 v158, v158
	v_rcp_f32_e32 v159, v159
	v_rcp_f32_e32 v164, v164
	v_rcp_f32_e32 v165, v165
	v_lshlrev_b32_e32 v166, 16, v232
	v_and_b32_e32 v167, 0xffff0000, v232
	v_lshlrev_b32_e32 v168, 16, v233
	v_and_b32_e32 v169, 0xffff0000, v233
	v_lshlrev_b32_e32 v170, 16, v234
	v_and_b32_e32 v171, 0xffff0000, v234
	v_lshlrev_b32_e32 v150, 16, v235
	v_and_b32_e32 v151, 0xffff0000, v235
	v_pk_mul_f32 v[154:155], v[154:155], v[166:167]
	v_pk_mul_f32 v[156:157], v[156:157], v[168:169]
	v_pk_mul_f32 v[158:159], v[158:159], v[170:171]
	v_pk_mul_f32 v[164:165], v[164:165], v[150:151]
	v_pk_mul_f32 v[6:7], v[6:7], v[154:155]
	v_pk_mul_f32 v[8:9], v[8:9], v[156:157]
	v_pk_mul_f32 v[2:3], v[2:3], v[158:159]
	v_pk_mul_f32 v[4:5], v[4:5], v[164:165]
	s_mov_b64 s[6:7], exec
.Lepi9_done:
.LBB0_1148:
	s_andn2_b64 vcc, exec, s[4:5]
	s_mov_b64 s[4:5], -1
	s_cbranch_vccnz .LBB0_1089
	s_and_b64 vcc, exec, s[6:7]
	s_cbranch_vccnz .LBB0_1151
	v_mov_b32_e32 v2, 0
	v_mov_b32_e32 v3, v2
	v_mov_b32_e32 v4, v2
	v_mov_b32_e32 v5, v2
	v_mov_b32_e32 v6, v2
	v_mov_b32_e32 v7, v2
	v_mov_b32_e32 v8, v2
	v_mov_b32_e32 v9, v2
	v_mov_b32_e32 v10, v2
	v_mov_b32_e32 v11, v2
	v_mov_b32_e32 v12, v2
	v_mov_b32_e32 v13, v2
	v_mov_b32_e32 v14, v2
	v_mov_b32_e32 v15, v2
	v_mov_b32_e32 v16, v2
	v_mov_b32_e32 v17, v2
	v_mov_b32_e32 v18, v2
	v_mov_b32_e32 v19, v2
	v_mov_b32_e32 v20, v2
	v_mov_b32_e32 v21, v2
	v_mov_b32_e32 v22, v2
	v_mov_b32_e32 v23, v2
	v_mov_b32_e32 v24, v2
	v_mov_b32_e32 v25, v2
	v_mov_b32_e32 v26, v2
	v_mov_b32_e32 v27, v2
	v_mov_b32_e32 v28, v2
	v_mov_b32_e32 v29, v2
	v_mov_b32_e32 v30, v2
	v_mov_b32_e32 v31, v2
	v_mov_b32_e32 v32, v2
	v_mov_b32_e32 v33, v2
	v_mov_b32_e32 v34, v2
	v_mov_b32_e32 v35, v2
	v_mov_b32_e32 v36, v2
	v_mov_b32_e32 v37, v2
	v_mov_b32_e32 v38, v2
	v_mov_b32_e32 v39, v2
	v_mov_b32_e32 v40, v2
	v_mov_b32_e32 v41, v2
	v_mov_b32_e32 v42, v2
	v_mov_b32_e32 v43, v2
	v_mov_b32_e32 v44, v2
	v_mov_b32_e32 v45, v2
	v_mov_b32_e32 v46, v2
	v_mov_b32_e32 v47, v2
	v_mov_b32_e32 v48, v2
	v_mov_b32_e32 v49, v2
	v_mov_b32_e32 v50, v2
	v_mov_b32_e32 v51, v2
	v_mov_b32_e32 v52, v2
	v_mov_b32_e32 v53, v2
	v_mov_b32_e32 v54, v2
	v_mov_b32_e32 v55, v2
	v_mov_b32_e32 v56, v2
	v_mov_b32_e32 v57, v2
	v_mov_b32_e32 v58, v2
	v_mov_b32_e32 v59, v2
	v_mov_b32_e32 v60, v2
	v_mov_b32_e32 v61, v2
	v_mov_b32_e32 v62, v2
	v_mov_b32_e32 v63, v2
	v_mov_b32_e32 v64, v2
	v_mov_b32_e32 v65, v2
	v_mov_b32_e32 v66, v2
	v_mov_b32_e32 v67, v2
	v_mov_b32_e32 v68, v2
	v_mov_b32_e32 v69, v2
	v_mov_b32_e32 v70, v2
	v_mov_b32_e32 v71, v2
	v_mov_b32_e32 v72, v2
	v_mov_b32_e32 v73, v2
	v_mov_b32_e32 v74, v2
	v_mov_b32_e32 v75, v2
	v_mov_b32_e32 v76, v2
	v_mov_b32_e32 v77, v2
	v_mov_b32_e32 v78, v2
	v_mov_b32_e32 v79, v2
	v_mov_b32_e32 v80, v2
	v_mov_b32_e32 v81, v2
	v_mov_b32_e32 v82, v2
	v_mov_b32_e32 v83, v2
	v_mov_b32_e32 v84, v2
	v_mov_b32_e32 v85, v2
	v_mov_b32_e32 v86, v2
	v_mov_b32_e32 v87, v2
	v_mov_b32_e32 v88, v2
	v_mov_b32_e32 v89, v2
	v_mov_b32_e32 v90, v2
	v_mov_b32_e32 v91, v2
	v_mov_b32_e32 v92, v2
	v_mov_b32_e32 v93, v2
	v_mov_b32_e32 v94, v2
	v_mov_b32_e32 v95, v2
	v_mov_b32_e32 v96, v2
	v_mov_b32_e32 v97, v2
	v_mov_b32_e32 v98, v2
	v_mov_b32_e32 v99, v2
	v_mov_b32_e32 v100, v2
	v_mov_b32_e32 v101, v2
	v_mov_b32_e32 v102, v2
	v_mov_b32_e32 v103, v2
	v_mov_b32_e32 v104, v2
	v_mov_b32_e32 v105, v2
	v_mov_b32_e32 v106, v2
	v_mov_b32_e32 v107, v2
	v_mov_b32_e32 v108, v2
	v_mov_b32_e32 v109, v2
	v_mov_b32_e32 v110, v2
	v_mov_b32_e32 v111, v2
	v_mov_b32_e32 v112, v2
	v_mov_b32_e32 v113, v2
	v_mov_b32_e32 v114, v2
	v_mov_b32_e32 v115, v2
	v_mov_b32_e32 v116, v2
	v_mov_b32_e32 v117, v2
	v_mov_b32_e32 v118, v2
	v_mov_b32_e32 v119, v2
	v_mov_b32_e32 v120, v2
	v_mov_b32_e32 v121, v2
	v_mov_b32_e32 v122, v2
	v_mov_b32_e32 v123, v2
	v_mov_b32_e32 v124, v2
	v_mov_b32_e32 v125, v2
	v_mov_b32_e32 v126, v2
	v_mov_b32_e32 v127, v2
	v_mov_b32_e32 v128, v2
	v_mov_b32_e32 v129, v2
.LBB0_1151:
	s_andn2_b64 vcc, exec, s[10:11]
	s_cbranch_vccnz .LBB0_1088
	s_barrier
	s_branch .LBB0_1088
.LBB0_1169:
	s_waitcnt vmcnt(0)
	v_readlane_b32 s0, v240, 22
	v_readlane_b32 s1, v240, 23
	s_barrier
